# stack: v_mov_b64 accumulator zeroing (G1,G4) + no store drain between ssd_sample and GP + tails dealt over all workgroups
# speedup vs baseline: 1.0002x; 1.0002x over previous
; template <class Epi>
; __device__ __forceinline__ void gemm_phase(LAS unsigned char* lds_in, int wave_in, const Gemm g, const StaticOrder& S, const Epi& E) {
;     ...
;         const char* nA = has_next ? (const char*)g.A + (size_t)nxt.pm * tstepA + (size_t)nxt.pn * g.a_pn_off * 2 : cA; const char* nB = has_next ? (const char*)g.Bt + (size_t)nxt.pn * tstepB : cB;
;     ...
;         if (!has_next) break;
; #pragma unroll
;         for (int a = 0; a < 2; ++a)
; #pragma unroll
;             for (int b = 0; b < 2; ++b)
; #pragma unroll
;                 for (int m = 0; m < 4; ++m)
; #pragma unroll
;                     for (int n = 0; n < 2; ++n) acc[a][b][m][n] = (f32x4){0.f, 0.f, 0.f, 0.f};
;         cur = nxt; cA = nA; cB = nB; ++ui;
.LBB0_275:
	s_ashr_i32 s19, s18, 31
	s_lshl_b64 s[0:1], s[18:19], 19
	s_add_u32 s20, s36, s0
	s_addc_u32 s21, s37, s1
	s_and_b64 s[0:1], s[2:3], exec
	s_cselect_b32 s0, s21, s27
	s_cselect_b32 s1, s20, s26
	s_ashr_i32 s17, s16, 31
	s_lshl_b64 s[22:23], s[16:17], 19
	s_add_u32 s22, s38, s22
	s_addc_u32 s23, s39, s23
	s_and_b64 s[30:31], s[2:3], exec
	s_cselect_b32 s5, s23, s29
	s_cselect_b32 s17, s22, s28
	s_add_u32 s26, s26, 0x40080
	s_addc_u32 s27, s27, 0
	s_add_u32 s19, s28, 0x100
	v_mov_b64_e32 v[2:3], 0
	v_mov_b64_e32 v[4:5], 0
	v_mov_b64_e32 v[6:7], 0
	v_mov_b64_e32 v[8:9], 0
	v_mov_b64_e32 v[10:11], 0
	v_mov_b64_e32 v[12:13], 0
	v_mov_b64_e32 v[14:15], 0
	v_mov_b64_e32 v[16:17], 0
	v_mov_b64_e32 v[18:19], 0
	v_mov_b64_e32 v[20:21], 0
	v_mov_b64_e32 v[22:23], 0
	v_mov_b64_e32 v[24:25], 0
	v_mov_b64_e32 v[26:27], 0
	v_mov_b64_e32 v[28:29], 0
	v_mov_b64_e32 v[30:31], 0
	v_mov_b64_e32 v[32:33], 0
	v_mov_b64_e32 v[34:35], 0
	v_mov_b64_e32 v[36:37], 0
	v_mov_b64_e32 v[38:39], 0
	v_mov_b64_e32 v[40:41], 0
	v_mov_b64_e32 v[42:43], 0
	v_mov_b64_e32 v[44:45], 0
	v_mov_b64_e32 v[46:47], 0
	v_mov_b64_e32 v[48:49], 0
	v_mov_b64_e32 v[50:51], 0
	v_mov_b64_e32 v[52:53], 0
	v_mov_b64_e32 v[54:55], 0
	v_mov_b64_e32 v[56:57], 0
	v_mov_b64_e32 v[58:59], 0
	v_mov_b64_e32 v[60:61], 0
	v_mov_b64_e32 v[62:63], 0
	v_mov_b64_e32 v[64:65], 0
	v_mov_b64_e32 v[66:67], 0
	v_mov_b64_e32 v[68:69], 0
	v_mov_b64_e32 v[70:71], 0
	v_mov_b64_e32 v[72:73], 0
	v_mov_b64_e32 v[74:75], 0
	v_mov_b64_e32 v[76:77], 0
	v_mov_b64_e32 v[78:79], 0
	v_mov_b64_e32 v[80:81], 0
	v_mov_b64_e32 v[82:83], 0
	v_mov_b64_e32 v[84:85], 0
	v_mov_b64_e32 v[86:87], 0
	v_mov_b64_e32 v[88:89], 0
	v_mov_b64_e32 v[90:91], 0
	v_mov_b64_e32 v[92:93], 0
	v_mov_b64_e32 v[94:95], 0
	v_mov_b64_e32 v[96:97], 0
	v_mov_b64_e32 v[98:99], 0
	v_mov_b64_e32 v[100:101], 0
	v_mov_b64_e32 v[102:103], 0
	v_mov_b64_e32 v[104:105], 0
	v_mov_b64_e32 v[106:107], 0
	v_mov_b64_e32 v[108:109], 0
	v_mov_b64_e32 v[110:111], 0
	v_mov_b64_e32 v[112:113], 0
	v_mov_b64_e32 v[114:115], 0
	v_mov_b64_e32 v[116:117], 0
	v_mov_b64_e32 v[118:119], 0
	v_mov_b64_e32 v[120:121], 0
	v_mov_b64_e32 v[122:123], 0
	v_mov_b64_e32 v[124:125], 0
	v_mov_b64_e32 v[126:127], 0
	v_mov_b64_e32 v[128:129], 0
	s_addc_u32 s33, s29, 0
	s_mov_b32 s58, -2

; __device__ __forceinline__ KP kparams() { KP p = (KP)__builtin_amdgcn_kernarg_segment_ptr(); asm volatile("" : "+s"(p)); return p; }
; #define LG_(x) ({ int v_ = (x); asm volatile("" : "+s"(v_)); v_; })
; template <class Epi>
; __device__ __forceinline__ void gemm_phase(LAS unsigned char* lds_in, int wave_in, const Gemm g, const StaticOrder& S, const Epi& E) {
;     ...
;     Unit cur, nxt; int ui = 0;
;     if (!S.next(0, cur)) return;
; __global__ void __launch_bounds__(NTHREADS, 2) hybrid_fwd(Params P) {
;     ...
;         __syncthreads();
;         { KP kp = kparams(); unsigned char* ws = kp->ws; pg8::StaticOrder S;
;           pg8::Gemm g{WSP(bf16_t, WS_DBUF), WSP(bf16_t, WS_PWT) + (size_t)l * 1024 * 256, 1024, 256, 256, 256}; S.init(MP, 1024, LG_(C.G), LG_(C.bid));
;           pg8::EpiScale E{WSP(bf16_t, WS_POOLED), 1024, nullptr, nullptr, -1};
;           pg8::gemm_phase(lds, C.wave, g, S, E); }
.LBB0_733:
	v_readlane_b32 s2, v255, 3
	v_readlane_b32 s3, v255, 4
	s_mov_b32 s0, s74
	s_mov_b32 s1, s70
	s_waitcnt lgkmcnt(0)
	s_barrier
	v_mov_b32_e32 v10, v174
	s_mov_b32 s10, s75
	s_mov_b32 s12, s77
	s_cmpk_gt_i32 s1, 0x113
	s_mov_b32 s50, 0x10000
	s_mov_b32 s51, 0x18000
	s_mov_b32 s29, 0x8000
	s_movk_i32 s33, 0x88f
	s_movk_i32 s38, 0x80f
	s_mov_b32 s48, 0x30000
	s_mov_b32 s49, 0x20000
	s_movk_i32 s39, 0x1600
	s_movk_i32 s42, 0x27f
	s_cbranch_scc1 .LBB0_761
	s_ashr_i32 s33, s1, 31
	s_lshr_b32 s4, s33, 29
	s_add_i32 s8, s1, s4
	s_and_b32 s4, s8, -8
	s_sub_i32 s7, s1, s4
	s_cmp_gt_i32 s7, 3
	s_mov_b64 s[4:5], -1
	s_cbranch_scc0 .LBB0_736
	s_mul_i32 s4, s7, 34
	s_add_i32 s6, s4, 4
	s_mov_b64 s[4:5], 0

; template <class Epi>
; __device__ __forceinline__ void gemm_phase(LAS unsigned char* lds_in, int wave_in, const Gemm g, const StaticOrder& S, const Epi& E) {
;     ...
;         const char* nA = has_next ? (const char*)g.A + (size_t)nxt.pm * tstepA + (size_t)nxt.pn * g.a_pn_off * 2 : cA; const char* nB = has_next ? (const char*)g.Bt + (size_t)nxt.pn * tstepB : cB;
;     ...
;         if (!has_next) break;
; #pragma unroll
;         for (int a = 0; a < 2; ++a)
; #pragma unroll
;             for (int b = 0; b < 2; ++b)
; #pragma unroll
;                 for (int m = 0; m < 4; ++m)
; #pragma unroll
;                     for (int n = 0; n < 2; ++n) acc[a][b][m][n] = (f32x4){0.f, 0.f, 0.f, 0.f};
;         cur = nxt; cA = nA; cB = nB; ++ui;
.LBB0_1096:
	s_ashr_i32 s15, s14, 31
	s_lshl_b64 s[16:17], s[14:15], 19
	s_add_u32 s16, s31, s16
	s_addc_u32 s17, s34, s17
	s_and_b64 s[18:19], s[2:3], exec
	s_cselect_b32 s1, s17, s23
	s_cselect_b32 s15, s16, s22
	s_ashr_i32 s13, s12, 31
	s_lshl_b64 s[18:19], s[12:13], 19
	s_add_u32 s18, s35, s18
	s_addc_u32 s19, s36, s19
	s_and_b64 s[26:27], s[2:3], exec
	s_cselect_b32 s13, s19, s25
	s_cselect_b32 s21, s18, s24
	s_add_u32 s22, s22, 0x40080
	s_addc_u32 s23, s23, 0
	s_add_u32 s33, s24, 0x100
	v_mov_b64_e32 v[2:3], 0
	v_mov_b64_e32 v[4:5], 0
	v_mov_b64_e32 v[6:7], 0
	v_mov_b64_e32 v[8:9], 0
	v_mov_b64_e32 v[10:11], 0
	v_mov_b64_e32 v[12:13], 0
	v_mov_b64_e32 v[14:15], 0
	v_mov_b64_e32 v[16:17], 0
	v_mov_b64_e32 v[18:19], 0
	v_mov_b64_e32 v[20:21], 0
	v_mov_b64_e32 v[22:23], 0
	v_mov_b64_e32 v[24:25], 0
	v_mov_b64_e32 v[26:27], 0
	v_mov_b64_e32 v[28:29], 0
	v_mov_b64_e32 v[30:31], 0
	v_mov_b64_e32 v[32:33], 0
	v_mov_b64_e32 v[34:35], 0
	v_mov_b64_e32 v[36:37], 0
	v_mov_b64_e32 v[38:39], 0
	v_mov_b64_e32 v[40:41], 0
	v_mov_b64_e32 v[42:43], 0
	v_mov_b64_e32 v[44:45], 0
	v_mov_b64_e32 v[46:47], 0
	v_mov_b64_e32 v[48:49], 0
	v_mov_b64_e32 v[50:51], 0
	v_mov_b64_e32 v[52:53], 0
	v_mov_b64_e32 v[54:55], 0
	v_mov_b64_e32 v[56:57], 0
	v_mov_b64_e32 v[58:59], 0
	v_mov_b64_e32 v[60:61], 0
	v_mov_b64_e32 v[62:63], 0
	v_mov_b64_e32 v[64:65], 0
	v_mov_b64_e32 v[66:67], 0
	v_mov_b64_e32 v[68:69], 0
	v_mov_b64_e32 v[70:71], 0
	v_mov_b64_e32 v[72:73], 0
	v_mov_b64_e32 v[74:75], 0
	v_mov_b64_e32 v[76:77], 0
	v_mov_b64_e32 v[78:79], 0
	v_mov_b64_e32 v[80:81], 0
	v_mov_b64_e32 v[82:83], 0
	v_mov_b64_e32 v[84:85], 0
	v_mov_b64_e32 v[86:87], 0
	v_mov_b64_e32 v[88:89], 0
	v_mov_b64_e32 v[90:91], 0
	v_mov_b64_e32 v[92:93], 0
	v_mov_b64_e32 v[94:95], 0
	v_mov_b64_e32 v[96:97], 0
	v_mov_b64_e32 v[98:99], 0
	v_mov_b64_e32 v[100:101], 0
	v_mov_b64_e32 v[102:103], 0
	v_mov_b64_e32 v[104:105], 0
	v_mov_b64_e32 v[106:107], 0
	v_mov_b64_e32 v[108:109], 0
	v_mov_b64_e32 v[110:111], 0
	v_mov_b64_e32 v[112:113], 0
	v_mov_b64_e32 v[114:115], 0
	v_mov_b64_e32 v[116:117], 0
	v_mov_b64_e32 v[118:119], 0
	v_mov_b64_e32 v[120:121], 0
	v_mov_b64_e32 v[122:123], 0
	v_mov_b64_e32 v[124:125], 0
	v_mov_b64_e32 v[126:127], 0
	v_mov_b64_e32 v[128:129], 0
	s_addc_u32 s58, s25, 0
	s_mov_b32 s59, -2
